# rwkv head loop: next head's z operand lines warmed in L2 by register-free dummy LDS-DMA loads issued with the current head's loads; plus previous edits
# baseline (speedup 1.0000x reference)
; #define GAS __attribute__((address_space(1)))
; DI void rwkv_fused_phase(const Frame& F, const CAS Args& a, int l) {
;     ...
;             for (int q = 0; q < 2; ++q) pvf[q] = *(const GAS f32x4*)(P.VF + po + 4 * q);
; #pragma unroll
;             for (int which = 0; which < 3; ++which) { const int zc = (which == 0 ? ZC_R : (which == 1 ? ZC_K : ZC_V)) + ch;
;                 zc_[which] = *(const GAS u32x4*)(Z + (size_t)gr * ZP + zc); zp_[which] = *(const GAS u32x4*)(Z + (size_t)(gr > 0 ? gr - 1 : 0) * ZP + zc); }
.LBB0_657:
	s_mov_b32 m0, 0x25900
	v_ashrrev_i32_e32 v1, 31, v0
	v_mov_b32_e32 v121, v185
	v_lshlrev_b64 v[0:1], 1, v[0:1]
	v_lshl_add_u64 v[122:123], v[120:121], 2, s[38:39]
	v_lshl_add_u64 v[2:3], v[66:67], 0, v[0:1]
	s_movk_i32 s0, 0x1000
	global_load_dwordx4 v[52:55], v[122:123], off offset:16
	global_load_dwordx4 v[56:59], v[122:123], off
	v_lshl_add_u64 v[0:1], v[116:117], 0, v[0:1]
	global_load_dwordx4 v[40:43], v[2:3], off offset:1536
	global_load_dwordx4 v[32:35], v[2:3], off offset:2816
	global_load_dwordx4 v[36:39], v[0:1], off offset:1536
	global_load_dwordx4 v[24:27], v[0:1], off offset:2816
	global_load_lds_dword v[2:3], off offset:1664
	global_load_lds_dword v[2:3], off offset:2944
	global_load_lds_dword v[0:1], off offset:1664
	global_load_lds_dword v[0:1], off offset:2944
	v_add_co_u32_e32 v2, vcc, s0, v2
	s_movk_i32 s60, 0x1000
	s_nop 0
	v_addc_co_u32_e32 v3, vcc, 0, v3, vcc
	v_add_co_u32_e32 v0, vcc, s0, v0
	s_nop 1
	v_addc_co_u32_e32 v1, vcc, 0, v1, vcc
	global_load_dwordx4 v[4:7], v[2:3], off
	global_load_dwordx4 v[188:191], v[0:1], off
	global_load_lds_dword v[2:3], off offset:128
	global_load_lds_dword v[0:1], off offset:128
	s_and_saveexec_b64 s[10:11], s[46:47]
	s_cbranch_execz .LBB0_655
	s_mov_b32 s9, s21
	s_lshl_b64 s[0:1], s[8:9], 2
	v_lshl_add_u64 v[44:45], v[80:81], 0, s[0:1]
	v_lshl_add_u64 v[46:47], v[82:83], 0, s[0:1]
	v_lshl_add_u64 v[48:49], v[84:85], 0, s[0:1]
	v_lshl_add_u64 v[50:51], v[86:87], 0, s[0:1]
	v_lshl_add_u64 v[28:29], v[88:89], 0, s[0:1]
	v_lshl_add_u64 v[30:31], v[90:91], 0, s[0:1]
	v_or_b32_e32 v196, s8, v128
	s_mov_b64 s[36:37], 0
	v_mov_b32_e32 v20, v176
	v_mov_b32_e32 v21, v74
	s_branch .LBB0_630
